# speedup vs baseline: 1.0180x; 1.0075x over previous
; __device__ __forceinline__ void gemm_tile(const TileDesc& td, char* shm_c, const int wv) {
;     ...
;   } else if (mode == EPI_RESID) {
;     #pragma unroll
;     for (int ai = 0; ai < 2; ++ai)
;     #pragma unroll
;     for (int bj = 0; bj < 2; ++bj)
;     #pragma unroll
;     for (int m = 0; m < 4; ++m)
;     #pragma unroll
;     for (int n = 0; n < 2; ++n) {
;       long o = (long)(td.bcol + bj * 128 + n * 16 + br_l) * D + (td.brow + ai * 128 + m * 16 + ar_l);
;       float4 r = *(const float4*)(td.aux + o);
;       f32x4 v = acc[ai][bj][m][n];
;       r.x += v[0]; r.y += v[1]; r.z += v[2]; r.w += v[3];
;       *(float4*)(td.outf + o) = r;
;     }
.LBB0_498:
	v_mbcnt_lo_u32_b32 v128, -1, 0
	v_mbcnt_hi_u32_b32 v128, -1, v128
	s_sext_i32_i16 s27, s27
	v_lshrrev_b32_e32 v130, 2, v128
	v_and_or_b32 v128, v128, 15, s42
	v_and_or_b32 v132, v130, 12, s38
	v_lshl_or_b32 v140, s27, 8, v128
	v_ashrrev_i32_e32 v141, 31, v140
	v_lshl_add_u32 v132, s26, 8, v132
	v_lshlrev_b64 v[130:131], 12, v[140:141]
	v_ashrrev_i32_e32 v133, 31, v132
	v_lshl_add_u64 v[134:135], v[130:131], 0, v[132:133]
	v_lshlrev_b64 v[144:145], 2, v[134:135]
	v_lshl_add_u64 v[146:147], s[72:73], 0, v[144:145]
	v_lshl_add_u64 v[148:149], s[70:71], 0, v[144:145]
	v_add_co_u32_e32 v150, vcc, 0x40000, v146
	s_nop 1
	v_addc_co_u32_e32 v151, vcc, 0, v147, vcc
	v_add_co_u32_e32 v156, vcc, 0x40000, v148
	s_nop 1
	v_addc_co_u32_e32 v157, vcc, 0, v149, vcc
	v_add_co_u32_e32 v152, vcc, 0x200000, v146
	s_nop 1
	v_addc_co_u32_e32 v153, vcc, 0, v147, vcc
	v_add_co_u32_e32 v158, vcc, 0x200000, v148
	s_nop 1
	v_addc_co_u32_e32 v159, vcc, 0, v149, vcc
	v_add_co_u32_e32 v154, vcc, 0x240000, v146
	s_nop 1
	v_addc_co_u32_e32 v155, vcc, 0, v147, vcc
	v_add_co_u32_e32 v160, vcc, 0x240000, v148
	s_nop 1
	v_addc_co_u32_e32 v161, vcc, 0, v149, vcc
	s_add_i32 s59, s59, s91
	s_cmpk_lt_i32 s59, 0x400
	v_readlane_b32 s67, v255, 34
	global_load_dwordx4 v[164:167], v[146:147], off
	global_load_dwordx4 v[168:171], v[150:151], off
	global_load_dwordx4 v[172:175], v[146:147], off offset:64
	global_load_dwordx4 v[176:179], v[150:151], off offset:64
	global_load_dwordx4 v[180:183], v[146:147], off offset:128
	global_load_dwordx4 v[184:187], v[150:151], off offset:128
	global_load_dwordx4 v[188:191], v[146:147], off offset:192
	global_load_dwordx4 v[192:195], v[150:151], off offset:192
	global_load_dwordx4 v[196:199], v[152:153], off
	global_load_dwordx4 v[200:203], v[154:155], off
	global_load_dwordx4 v[204:207], v[152:153], off offset:64
	global_load_dwordx4 v[208:211], v[154:155], off offset:64
	global_load_dwordx4 v[212:215], v[152:153], off offset:128
	global_load_dwordx4 v[216:219], v[154:155], off offset:128
	global_load_dwordx4 v[220:223], v[152:153], off offset:192
	global_load_dwordx4 v[224:227], v[154:155], off offset:192
	s_waitcnt vmcnt(15)
	v_pk_add_f32 v[124:125], v[124:125], v[164:165]
	v_pk_add_f32 v[126:127], v[126:127], v[166:167]
	global_store_dwordx4 v[148:149], v[124:127], off
	s_waitcnt vmcnt(15)
	v_pk_add_f32 v[120:121], v[120:121], v[168:169]
	v_pk_add_f32 v[122:123], v[122:123], v[170:171]
	global_store_dwordx4 v[156:157], v[120:123], off
	s_waitcnt vmcnt(15)
	v_pk_add_f32 v[116:117], v[116:117], v[172:173]
	v_pk_add_f32 v[118:119], v[118:119], v[174:175]
	global_store_dwordx4 v[148:149], v[116:119], off offset:64
	s_waitcnt vmcnt(15)
	v_pk_add_f32 v[112:113], v[112:113], v[176:177]
	v_pk_add_f32 v[114:115], v[114:115], v[178:179]
	global_store_dwordx4 v[156:157], v[112:115], off offset:64
	s_waitcnt vmcnt(15)
	v_pk_add_f32 v[108:109], v[108:109], v[180:181]
	v_pk_add_f32 v[110:111], v[110:111], v[182:183]
	global_store_dwordx4 v[148:149], v[108:111], off offset:128
	s_waitcnt vmcnt(15)
	v_pk_add_f32 v[104:105], v[104:105], v[184:185]
	v_pk_add_f32 v[106:107], v[106:107], v[186:187]
	global_store_dwordx4 v[156:157], v[104:107], off offset:128
	s_waitcnt vmcnt(15)
	v_pk_add_f32 v[100:101], v[100:101], v[188:189]
	v_pk_add_f32 v[102:103], v[102:103], v[190:191]
	global_store_dwordx4 v[148:149], v[100:103], off offset:192
	s_waitcnt vmcnt(15)
	v_pk_add_f32 v[96:97], v[96:97], v[192:193]
	v_pk_add_f32 v[98:99], v[98:99], v[194:195]
	global_store_dwordx4 v[156:157], v[96:99], off offset:192
	s_waitcnt vmcnt(15)
	v_pk_add_f32 v[92:93], v[92:93], v[196:197]
	v_pk_add_f32 v[94:95], v[94:95], v[198:199]
	global_store_dwordx4 v[158:159], v[92:95], off
	s_waitcnt vmcnt(15)
	v_pk_add_f32 v[88:89], v[88:89], v[200:201]
	v_pk_add_f32 v[90:91], v[90:91], v[202:203]
	global_store_dwordx4 v[160:161], v[88:91], off
	s_waitcnt vmcnt(15)
	v_pk_add_f32 v[84:85], v[84:85], v[204:205]
	v_pk_add_f32 v[86:87], v[86:87], v[206:207]
	global_store_dwordx4 v[158:159], v[84:87], off offset:64
	s_waitcnt vmcnt(15)
	v_pk_add_f32 v[80:81], v[80:81], v[208:209]
	v_pk_add_f32 v[82:83], v[82:83], v[210:211]
	global_store_dwordx4 v[160:161], v[80:83], off offset:64
	s_waitcnt vmcnt(15)
; __device__ __forceinline__ void gemm_tile(const TileDesc& td, char* shm_c, const int wv) {
;     ...
;   } else if (mode == EPI_RESID) {
;     #pragma unroll
;     for (int ai = 0; ai < 2; ++ai)
;     #pragma unroll
;     for (int bj = 0; bj < 2; ++bj)
;     #pragma unroll
;     for (int m = 0; m < 4; ++m)
;     #pragma unroll
;     for (int n = 0; n < 2; ++n) {
;       long o = (long)(td.bcol + bj * 128 + n * 16 + br_l) * D + (td.brow + ai * 128 + m * 16 + ar_l);
;       float4 r = *(const float4*)(td.aux + o);
;       f32x4 v = acc[ai][bj][m][n];
;       r.x += v[0]; r.y += v[1]; r.z += v[2]; r.w += v[3];
;       *(float4*)(td.outf + o) = r;
;     }
	v_pk_add_f32 v[76:77], v[76:77], v[212:213]
	v_pk_add_f32 v[78:79], v[78:79], v[214:215]
	global_store_dwordx4 v[158:159], v[76:79], off offset:128
	s_waitcnt vmcnt(15)
	v_pk_add_f32 v[72:73], v[72:73], v[216:217]
	v_pk_add_f32 v[74:75], v[74:75], v[218:219]
	global_store_dwordx4 v[160:161], v[72:75], off offset:128
	s_waitcnt vmcnt(15)
	v_pk_add_f32 v[68:69], v[68:69], v[220:221]
	v_pk_add_f32 v[70:71], v[70:71], v[222:223]
	global_store_dwordx4 v[158:159], v[68:71], off offset:192
	s_waitcnt vmcnt(15)
	v_pk_add_f32 v[64:65], v[64:65], v[224:225]
	v_pk_add_f32 v[66:67], v[66:67], v[226:227]
	global_store_dwordx4 v[160:161], v[64:67], off offset:192
	global_load_dwordx4 v[164:167], v[146:147], off offset:512
	global_load_dwordx4 v[168:171], v[150:151], off offset:512
	global_load_dwordx4 v[172:175], v[146:147], off offset:576
	global_load_dwordx4 v[176:179], v[150:151], off offset:576
	global_load_dwordx4 v[180:183], v[146:147], off offset:640
	global_load_dwordx4 v[184:187], v[150:151], off offset:640
	global_load_dwordx4 v[188:191], v[146:147], off offset:704
	global_load_dwordx4 v[192:195], v[150:151], off offset:704
	global_load_dwordx4 v[196:199], v[152:153], off offset:512
	global_load_dwordx4 v[200:203], v[154:155], off offset:512
	global_load_dwordx4 v[204:207], v[152:153], off offset:576
	global_load_dwordx4 v[208:211], v[154:155], off offset:576
	global_load_dwordx4 v[212:215], v[152:153], off offset:640
	global_load_dwordx4 v[216:219], v[154:155], off offset:640
	global_load_dwordx4 v[220:223], v[152:153], off offset:704
	global_load_dwordx4 v[224:227], v[154:155], off offset:704
	s_waitcnt vmcnt(15)
	v_pk_add_f32 v[60:61], v[60:61], v[164:165]
	v_pk_add_f32 v[62:63], v[62:63], v[166:167]
	global_store_dwordx4 v[148:149], v[60:63], off offset:512
	s_waitcnt vmcnt(15)
	v_pk_add_f32 v[56:57], v[56:57], v[168:169]
	v_pk_add_f32 v[58:59], v[58:59], v[170:171]
	global_store_dwordx4 v[156:157], v[56:59], off offset:512
	s_waitcnt vmcnt(15)
	v_pk_add_f32 v[52:53], v[52:53], v[172:173]
	v_pk_add_f32 v[54:55], v[54:55], v[174:175]
	global_store_dwordx4 v[148:149], v[52:55], off offset:576
	s_waitcnt vmcnt(15)
	v_pk_add_f32 v[48:49], v[48:49], v[176:177]
	v_pk_add_f32 v[50:51], v[50:51], v[178:179]
	global_store_dwordx4 v[156:157], v[48:51], off offset:576
	s_waitcnt vmcnt(15)
	v_pk_add_f32 v[44:45], v[44:45], v[180:181]
	v_pk_add_f32 v[46:47], v[46:47], v[182:183]
	global_store_dwordx4 v[148:149], v[44:47], off offset:640
	s_waitcnt vmcnt(15)
	v_pk_add_f32 v[40:41], v[40:41], v[184:185]
	v_pk_add_f32 v[42:43], v[42:43], v[186:187]
	global_store_dwordx4 v[156:157], v[40:43], off offset:640
	s_waitcnt vmcnt(15)
	v_pk_add_f32 v[36:37], v[36:37], v[188:189]
	v_pk_add_f32 v[38:39], v[38:39], v[190:191]
	global_store_dwordx4 v[148:149], v[36:39], off offset:704
	s_waitcnt vmcnt(15)
	v_pk_add_f32 v[32:33], v[32:33], v[192:193]
	v_pk_add_f32 v[34:35], v[34:35], v[194:195]
	global_store_dwordx4 v[156:157], v[32:35], off offset:704
	s_waitcnt vmcnt(15)
	v_pk_add_f32 v[28:29], v[28:29], v[196:197]
	v_pk_add_f32 v[30:31], v[30:31], v[198:199]
	global_store_dwordx4 v[158:159], v[28:31], off offset:512
	s_waitcnt vmcnt(15)
	v_pk_add_f32 v[24:25], v[24:25], v[200:201]
	v_pk_add_f32 v[26:27], v[26:27], v[202:203]
	global_store_dwordx4 v[160:161], v[24:27], off offset:512
	s_waitcnt vmcnt(15)
	v_pk_add_f32 v[20:21], v[20:21], v[204:205]
	v_pk_add_f32 v[22:23], v[22:23], v[206:207]
	global_store_dwordx4 v[158:159], v[20:23], off offset:576
	s_waitcnt vmcnt(15)
	v_pk_add_f32 v[16:17], v[16:17], v[208:209]
	v_pk_add_f32 v[18:19], v[18:19], v[210:211]
	global_store_dwordx4 v[160:161], v[16:19], off offset:576
	s_waitcnt vmcnt(15)
	v_pk_add_f32 v[12:13], v[12:13], v[212:213]
	v_pk_add_f32 v[14:15], v[14:15], v[214:215]
	global_store_dwordx4 v[158:159], v[12:15], off offset:640
	s_waitcnt vmcnt(15)
	v_pk_add_f32 v[8:9], v[8:9], v[216:217]
	v_pk_add_f32 v[10:11], v[10:11], v[218:219]
	global_store_dwordx4 v[160:161], v[8:11], off offset:640
	s_waitcnt vmcnt(15)
	v_pk_add_f32 v[4:5], v[4:5], v[220:221]
	v_pk_add_f32 v[6:7], v[6:7], v[222:223]
	global_store_dwordx4 v[158:159], v[4:7], off offset:704
	s_waitcnt vmcnt(15)
	v_pk_add_f32 v[0:1], v[0:1], v[224:225]
	v_pk_add_f32 v[2:3], v[2:3], v[226:227]
	global_store_dwordx4 v[160:161], v[0:3], off offset:704
	s_cbranch_scc0 .LBB0_509

; __device__ __forceinline__ void gemm_tile(const TileDesc& td, char* shm_c, const int wv) {
;     ...
;   } else if (mode == EPI_RESID) {
;     #pragma unroll
;     for (int ai = 0; ai < 2; ++ai)
;     #pragma unroll
;     for (int bj = 0; bj < 2; ++bj)
;     #pragma unroll
;     for (int m = 0; m < 4; ++m)
;     #pragma unroll
;     for (int n = 0; n < 2; ++n) {
;       long o = (long)(td.bcol + bj * 128 + n * 16 + br_l) * D + (td.brow + ai * 128 + m * 16 + ar_l);
;       float4 r = *(const float4*)(td.aux + o);
;       f32x4 v = acc[ai][bj][m][n];
;       r.x += v[0]; r.y += v[1]; r.z += v[2]; r.w += v[3];
;       *(float4*)(td.outf + o) = r;
;     }
; __device__ __forceinline__ void gemm_stage(const Params& p, int s, char* smem, const int wv) {
;     ...
;       td.mode = EPI_RESID; td.aux = p.out; td.outf = p.out;
.LBB0_772:
	v_mbcnt_lo_u32_b32 v128, -1, 0
	v_mbcnt_hi_u32_b32 v128, -1, v128
	s_sext_i32_i16 s25, s25
	v_lshrrev_b32_e32 v130, 2, v128
	v_and_or_b32 v128, v128, 15, s42
	v_lshl_or_b32 v140, s25, 8, v128
	v_and_or_b32 v130, v130, 12, s38
	v_ashrrev_i32_e32 v141, 31, v140
	v_lshl_add_u32 v130, s24, 8, v130
	v_ashrrev_i32_e32 v131, 31, v130
	v_lshlrev_b64 v[132:133], 14, v[140:141]
	v_lshl_add_u64 v[132:133], s[70:71], 0, v[132:133]
	v_lshlrev_b64 v[148:149], 2, v[130:131]
	v_lshl_add_u64 v[132:133], v[132:133], 0, v[148:149]
	v_add_co_u32_e32 v134, vcc, 0x40000, v132
	s_nop 1
	v_addc_co_u32_e32 v135, vcc, 0, v133, vcc
	v_add_co_u32_e32 v136, vcc, 0x200000, v132
	s_nop 1
	v_addc_co_u32_e32 v137, vcc, 0, v133, vcc
	v_add_co_u32_e32 v138, vcc, 0x240000, v132
	s_nop 1
	v_addc_co_u32_e32 v139, vcc, 0, v133, vcc
	s_add_i32 s83, s83, s91
	s_cmpk_lt_i32 s83, 0x400
	global_load_dwordx4 v[144:147], v[132:133], off
	global_load_dwordx4 v[148:151], v[134:135], off
	global_load_dwordx4 v[152:155], v[132:133], off offset:64
	global_load_dwordx4 v[156:159], v[134:135], off offset:64
	global_load_dwordx4 v[160:163], v[132:133], off offset:128
	global_load_dwordx4 v[164:167], v[134:135], off offset:128
	global_load_dwordx4 v[168:171], v[132:133], off offset:192
	global_load_dwordx4 v[172:175], v[134:135], off offset:192
	global_load_dwordx4 v[176:179], v[136:137], off
	global_load_dwordx4 v[180:183], v[138:139], off
	global_load_dwordx4 v[184:187], v[136:137], off offset:64
	global_load_dwordx4 v[188:191], v[138:139], off offset:64
	global_load_dwordx4 v[192:195], v[136:137], off offset:128
	global_load_dwordx4 v[196:199], v[138:139], off offset:128
	global_load_dwordx4 v[200:203], v[136:137], off offset:192
	global_load_dwordx4 v[204:207], v[138:139], off offset:192
	s_waitcnt vmcnt(15)
	v_pk_add_f32 v[124:125], v[124:125], v[144:145]
	v_pk_add_f32 v[126:127], v[126:127], v[146:147]
	global_store_dwordx4 v[132:133], v[124:127], off
	s_waitcnt vmcnt(15)
	v_pk_add_f32 v[120:121], v[120:121], v[148:149]
	v_pk_add_f32 v[122:123], v[122:123], v[150:151]
	global_store_dwordx4 v[134:135], v[120:123], off
	s_waitcnt vmcnt(15)
	v_pk_add_f32 v[112:113], v[112:113], v[152:153]
	v_pk_add_f32 v[114:115], v[114:115], v[154:155]
	global_store_dwordx4 v[132:133], v[112:115], off offset:64
	s_waitcnt vmcnt(15)
	v_pk_add_f32 v[116:117], v[116:117], v[156:157]
	v_pk_add_f32 v[118:119], v[118:119], v[158:159]
	global_store_dwordx4 v[134:135], v[116:119], off offset:64
	s_waitcnt vmcnt(15)
	v_pk_add_f32 v[104:105], v[104:105], v[160:161]
	v_pk_add_f32 v[106:107], v[106:107], v[162:163]
	global_store_dwordx4 v[132:133], v[104:107], off offset:128
	s_waitcnt vmcnt(15)
	v_pk_add_f32 v[108:109], v[108:109], v[164:165]
	v_pk_add_f32 v[110:111], v[110:111], v[166:167]
	global_store_dwordx4 v[134:135], v[108:111], off offset:128
	s_waitcnt vmcnt(15)
	v_pk_add_f32 v[96:97], v[96:97], v[168:169]
	v_pk_add_f32 v[98:99], v[98:99], v[170:171]
	global_store_dwordx4 v[132:133], v[96:99], off offset:192
	s_waitcnt vmcnt(15)
	v_pk_add_f32 v[100:101], v[100:101], v[172:173]
	v_pk_add_f32 v[102:103], v[102:103], v[174:175]
	global_store_dwordx4 v[134:135], v[100:103], off offset:192
	s_waitcnt vmcnt(15)
	v_pk_add_f32 v[88:89], v[88:89], v[176:177]
	v_pk_add_f32 v[90:91], v[90:91], v[178:179]
	global_store_dwordx4 v[136:137], v[88:91], off
	s_waitcnt vmcnt(15)
	v_pk_add_f32 v[92:93], v[92:93], v[180:181]
	v_pk_add_f32 v[94:95], v[94:95], v[182:183]
	global_store_dwordx4 v[138:139], v[92:95], off
	s_waitcnt vmcnt(15)
	v_pk_add_f32 v[80:81], v[80:81], v[184:185]
	v_pk_add_f32 v[82:83], v[82:83], v[186:187]
	global_store_dwordx4 v[136:137], v[80:83], off offset:64
	s_waitcnt vmcnt(15)
	v_pk_add_f32 v[84:85], v[84:85], v[188:189]
	v_pk_add_f32 v[86:87], v[86:87], v[190:191]
	global_store_dwordx4 v[138:139], v[84:87], off offset:64
	s_waitcnt vmcnt(15)
	v_pk_add_f32 v[72:73], v[72:73], v[192:193]
	v_pk_add_f32 v[74:75], v[74:75], v[194:195]
	global_store_dwordx4 v[136:137], v[72:75], off offset:128
	s_waitcnt vmcnt(15)
; __device__ __forceinline__ void gemm_tile(const TileDesc& td, char* shm_c, const int wv) {
;     ...
;   } else if (mode == EPI_RESID) {
;     #pragma unroll
;     for (int ai = 0; ai < 2; ++ai)
;     #pragma unroll
;     for (int bj = 0; bj < 2; ++bj)
;     #pragma unroll
;     for (int m = 0; m < 4; ++m)
;     #pragma unroll
;     for (int n = 0; n < 2; ++n) {
;       long o = (long)(td.bcol + bj * 128 + n * 16 + br_l) * D + (td.brow + ai * 128 + m * 16 + ar_l);
;       float4 r = *(const float4*)(td.aux + o);
;       f32x4 v = acc[ai][bj][m][n];
;       r.x += v[0]; r.y += v[1]; r.z += v[2]; r.w += v[3];
;       *(float4*)(td.outf + o) = r;
;     }
	v_pk_add_f32 v[76:77], v[76:77], v[196:197]
	v_pk_add_f32 v[78:79], v[78:79], v[198:199]
	global_store_dwordx4 v[138:139], v[76:79], off offset:128
	s_waitcnt vmcnt(15)
	v_pk_add_f32 v[64:65], v[64:65], v[200:201]
	v_pk_add_f32 v[66:67], v[66:67], v[202:203]
	global_store_dwordx4 v[136:137], v[64:67], off offset:192
	s_waitcnt vmcnt(15)
	v_pk_add_f32 v[68:69], v[68:69], v[204:205]
	v_pk_add_f32 v[70:71], v[70:71], v[206:207]
	global_store_dwordx4 v[138:139], v[68:71], off offset:192
	global_load_dwordx4 v[144:147], v[132:133], off offset:512
	global_load_dwordx4 v[148:151], v[134:135], off offset:512
	global_load_dwordx4 v[152:155], v[132:133], off offset:576
	global_load_dwordx4 v[156:159], v[134:135], off offset:576
	global_load_dwordx4 v[160:163], v[132:133], off offset:640
	global_load_dwordx4 v[164:167], v[134:135], off offset:640
	global_load_dwordx4 v[168:171], v[132:133], off offset:704
	global_load_dwordx4 v[172:175], v[134:135], off offset:704
	global_load_dwordx4 v[176:179], v[136:137], off offset:512
	global_load_dwordx4 v[180:183], v[138:139], off offset:512
	global_load_dwordx4 v[184:187], v[136:137], off offset:576
	global_load_dwordx4 v[188:191], v[138:139], off offset:576
	global_load_dwordx4 v[192:195], v[136:137], off offset:640
	global_load_dwordx4 v[196:199], v[138:139], off offset:640
	global_load_dwordx4 v[200:203], v[136:137], off offset:704
	global_load_dwordx4 v[204:207], v[138:139], off offset:704
	s_waitcnt vmcnt(15)
	v_pk_add_f32 v[56:57], v[56:57], v[144:145]
	v_pk_add_f32 v[58:59], v[58:59], v[146:147]
	global_store_dwordx4 v[132:133], v[56:59], off offset:512
	s_waitcnt vmcnt(15)
	v_pk_add_f32 v[60:61], v[60:61], v[148:149]
	v_pk_add_f32 v[62:63], v[62:63], v[150:151]
	global_store_dwordx4 v[134:135], v[60:63], off offset:512
	s_waitcnt vmcnt(15)
	v_pk_add_f32 v[48:49], v[48:49], v[152:153]
	v_pk_add_f32 v[50:51], v[50:51], v[154:155]
	global_store_dwordx4 v[132:133], v[48:51], off offset:576
	s_waitcnt vmcnt(15)
	v_pk_add_f32 v[52:53], v[52:53], v[156:157]
	v_pk_add_f32 v[54:55], v[54:55], v[158:159]
	global_store_dwordx4 v[134:135], v[52:55], off offset:576
	s_waitcnt vmcnt(15)
	v_pk_add_f32 v[40:41], v[40:41], v[160:161]
	v_pk_add_f32 v[42:43], v[42:43], v[162:163]
	global_store_dwordx4 v[132:133], v[40:43], off offset:640
	s_waitcnt vmcnt(15)
	v_pk_add_f32 v[44:45], v[44:45], v[164:165]
	v_pk_add_f32 v[46:47], v[46:47], v[166:167]
	global_store_dwordx4 v[134:135], v[44:47], off offset:640
	s_waitcnt vmcnt(15)
	v_pk_add_f32 v[32:33], v[32:33], v[168:169]
	v_pk_add_f32 v[34:35], v[34:35], v[170:171]
	global_store_dwordx4 v[132:133], v[32:35], off offset:704
	s_waitcnt vmcnt(15)
	v_pk_add_f32 v[36:37], v[36:37], v[172:173]
	v_pk_add_f32 v[38:39], v[38:39], v[174:175]
	global_store_dwordx4 v[134:135], v[36:39], off offset:704
	s_waitcnt vmcnt(15)
	v_pk_add_f32 v[24:25], v[24:25], v[176:177]
	v_pk_add_f32 v[26:27], v[26:27], v[178:179]
	global_store_dwordx4 v[136:137], v[24:27], off offset:512
	s_waitcnt vmcnt(15)
	v_pk_add_f32 v[28:29], v[28:29], v[180:181]
	v_pk_add_f32 v[30:31], v[30:31], v[182:183]
	global_store_dwordx4 v[138:139], v[28:31], off offset:512
	s_waitcnt vmcnt(15)
	v_pk_add_f32 v[16:17], v[16:17], v[184:185]
	v_pk_add_f32 v[18:19], v[18:19], v[186:187]
	global_store_dwordx4 v[136:137], v[16:19], off offset:576
	s_waitcnt vmcnt(15)
	v_pk_add_f32 v[20:21], v[20:21], v[188:189]
	v_pk_add_f32 v[22:23], v[22:23], v[190:191]
	global_store_dwordx4 v[138:139], v[20:23], off offset:576
	s_waitcnt vmcnt(15)
	v_pk_add_f32 v[8:9], v[8:9], v[192:193]
	v_pk_add_f32 v[10:11], v[10:11], v[194:195]
	global_store_dwordx4 v[136:137], v[8:11], off offset:640
	s_waitcnt vmcnt(15)
	v_pk_add_f32 v[12:13], v[12:13], v[196:197]
	v_pk_add_f32 v[14:15], v[14:15], v[198:199]
	global_store_dwordx4 v[138:139], v[12:15], off offset:640
	s_waitcnt vmcnt(15)
	v_pk_add_f32 v[0:1], v[0:1], v[200:201]
	v_pk_add_f32 v[2:3], v[2:3], v[202:203]
	global_store_dwordx4 v[136:137], v[0:3], off offset:704
	s_waitcnt vmcnt(15)
	v_pk_add_f32 v[4:5], v[4:5], v[204:205]
	v_pk_add_f32 v[6:7], v[6:7], v[206:207]
	global_store_dwordx4 v[138:139], v[4:7], off offset:704
	s_cbranch_scc0 .LBB0_783
